# P0 RMSNorm: norm-weight vector loaded once per wave before the row loop (v190-v253); the 16 per-row weight loads and their vmcnt(1)/vmcnt(0) waits (which also waited for each preceding store) removed
# baseline (speedup 1.0000x reference)
; __device__ __forceinline__ unsigned cvtpk(float lo, float hi) { f32x2_t v = {lo, hi}; bf16x2_t b = __builtin_convertvector(v, bf16x2_t); return __builtin_bit_cast(unsigned, b); }
; __device__ __forceinline__ void rms_regs_to_bf16(const f32x4 (&v)[16], const float* w, bf16* orow, int lane) {
;     float s = 0.f;
; #pragma unroll
;     for (int j = 0; j < 16; ++j) s += (v[j].x * v[j].x + v[j].y * v[j].y) + (v[j].z * v[j].z + v[j].w * v[j].w);
;     const float rstd = 1.0f / sqrtf(wave_sum(s) * (1.0f / DM) + EPS);
;     const f32x4* wr = (const f32x4*)w + 2 * lane; u32x4* o16 = (u32x4*)orow + lane;
; #pragma unroll
;     for (int j = 0; j < 8; ++j) { const f32x4 w0 = wr[128 * j], w1 = wr[128 * j + 1]; const f32x4 a = v[2 * j], b = v[2 * j + 1]; u32x4 o;
;         o.x = cvtpk(a.x * rstd * w0.x, a.y * rstd * w0.y); o.y = cvtpk(a.z * rstd * w0.z, a.w * rstd * w0.w); o.z = cvtpk(b.x * rstd * w1.x, b.y * rstd * w1.y); o.w = cvtpk(b.z * rstd * w1.z, b.w * rstd * w1.w); o16[64 * j] = o; }
; }
; __device__ __forceinline__ void rms_row_to_bf16(const float* xrow, const float* w, bf16* orow, int lane) {
;     const f32x4* xr = (const f32x4*)xrow + 2 * lane; f32x4 v[16];
; #pragma unroll
;     for (int j = 0; j < 8; ++j) { v[2 * j] = xr[128 * j]; v[2 * j + 1] = xr[128 * j + 1]; }
; __device__ __forceinline__ void p0_prologue(const Frame& F, const Ptrs& P) {
;     ...
;     for (int m = gw; m < M; m += NGW) { const float* xr = (m < MP) ? P_x_prompt + (size_t)m * DM : P_x_sample + (size_t)(m - MP) * DM; rms_row_to_bf16(xr, P_mix_nw, P_XN + (size_t)m * DM, F.lane); }
.LBB0_13:
	s_cmp_eq_u32 s98, 2
	s_cbranch_scc1 .LBB0_20x
	s_cmpk_gt_i32 s8, 0x23ff
	s_cbranch_scc1 .LBB0_20
	v_mbcnt_lo_u32_b32 v1, -1, 0
	v_mov_b32_e32 v67, 0
	v_lshlrev_b32_e32 v66, 4, v189
	v_mbcnt_hi_u32_b32 v3, -1, v1
	v_lshl_add_u64 v[4:5], s[50:51], 0, v[66:67]
	s_mov_b64 s[4:5], 0x10400000
	v_and_b32_e32 v1, 64, v3
	v_lshl_add_u64 v[68:69], v[4:5], 0, s[4:5]
	v_add_u32_e32 v4, 64, v1
	v_xor_b32_e32 v1, 1, v3
	v_cmp_lt_i32_e32 vcc, v1, v4
	v_xor_b32_e32 v5, 2, v3
	s_load_dwordx2 s[4:5], s[0:1], 0x40
	v_cndmask_b32_e32 v1, v3, v1, vcc
	v_cmp_lt_i32_e32 vcc, v5, v4
	v_lshlrev_b32_e32 v66, 5, v189
	v_lshlrev_b32_e32 v2, 1, v189
	v_cndmask_b32_e32 v5, v3, v5, vcc
	v_lshlrev_b32_e32 v85, 2, v5
	v_xor_b32_e32 v5, 4, v3
	v_cmp_lt_i32_e32 vcc, v5, v4
	s_waitcnt lgkmcnt(0)
	v_lshl_add_u64 v[70:71], s[4:5], 0, v[66:67]
	s_mov_b64 s[14:15], 0x1000
	v_cndmask_b32_e32 v5, v3, v5, vcc
	v_lshlrev_b32_e32 v86, 2, v5
	v_xor_b32_e32 v5, 8, v3
	v_cmp_lt_i32_e32 vcc, v5, v4
	s_mov_b64 s[16:17], 0x1800
	s_mov_b64 s[18:19], 0x2000
	v_cndmask_b32_e32 v5, v3, v5, vcc
	v_lshlrev_b32_e32 v87, 2, v5
	v_xor_b32_e32 v5, 16, v3
	v_cmp_lt_i32_e32 vcc, v5, v4
	s_mov_b64 s[20:21], 0x2800
	s_mov_b64 s[22:23], 0x3000
	v_cndmask_b32_e32 v5, v3, v5, vcc
	v_lshlrev_b32_e32 v88, 2, v5
	v_xor_b32_e32 v5, 32, v3
	v_cmp_lt_i32_e32 vcc, v5, v4
	s_mov_b64 s[24:25], 0x3800
	s_ashr_i32 s9, s8, 31
	v_cndmask_b32_e32 v3, v3, v5, vcc
	s_ashr_i32 s11, s10, 31
	s_mov_b32 s13, 0
	v_lshlrev_b32_e32 v1, 2, v1
	v_lshlrev_b32_e32 v89, 2, v3
	v_lshl_add_u64 v[72:73], v[70:71], 0, s[14:15]
	v_lshl_add_u64 v[74:75], v[70:71], 0, s[16:17]
	v_lshl_add_u64 v[76:77], v[70:71], 0, s[18:19]
	v_lshl_add_u64 v[78:79], v[70:71], 0, s[20:21]
	v_lshl_add_u64 v[80:81], v[70:71], 0, s[22:23]
	v_lshl_add_u64 v[82:83], v[70:71], 0, s[24:25]
	s_lshl_b64 s[26:27], s[8:9], 14
	s_lshl_b64 s[28:29], s[10:11], 14
	v_lshlrev_b32_e32 v66, 4, v2
	s_movk_i32 s33, 0x1000
	s_movk_i32 s36, 0x2000
	s_movk_i32 s37, 0x3000
	v_mov_b32_e32 v90, 0x358637bd
	s_mov_b32 s38, 0xf800000
	v_mov_b32_e32 v91, 0x260
	global_load_dwordx4 v[190:193], v[70:71], off
	global_load_dwordx4 v[194:197], v[70:71], off offset:16
	global_load_dwordx4 v[198:201], v[70:71], off offset:2048
	global_load_dwordx4 v[202:205], v[70:71], off offset:2064
	global_load_dwordx4 v[206:209], v[72:73], off
	global_load_dwordx4 v[210:213], v[72:73], off offset:16
	global_load_dwordx4 v[214:217], v[74:75], off
	global_load_dwordx4 v[218:221], v[74:75], off offset:16
	global_load_dwordx4 v[222:225], v[76:77], off
	global_load_dwordx4 v[226:229], v[76:77], off offset:16
	global_load_dwordx4 v[230:233], v[78:79], off
	global_load_dwordx4 v[234:237], v[78:79], off offset:16
	global_load_dwordx4 v[238:241], v[80:81], off
	global_load_dwordx4 v[242:245], v[80:81], off offset:16
	global_load_dwordx4 v[246:249], v[82:83], off
	global_load_dwordx4 v[250:253], v[82:83], off offset:16
	s_branch .LBB0_16
.LBB0_15:
	global_load_dwordx4 v[26:29], v66, s[4:5]
	global_load_dwordx4 v[22:25], v66, s[4:5] offset:16
	global_load_dwordx4 v[2:5], v66, s[4:5] offset:2064
	global_load_dwordx4 v[6:9], v66, s[4:5] offset:2048
	v_lshl_add_u64 v[10:11], s[4:5], 0, v[66:67]
	v_add_co_u32_e32 v12, vcc, 0x1000, v10
	v_lshl_add_u64 v[16:17], v[10:11], 0, s[16:17]
	s_nop 0
	v_addc_co_u32_e32 v13, vcc, 0, v11, vcc
	v_lshl_add_u64 v[14:15], v[10:11], 0, s[14:15]
	global_load_dwordx4 v[18:21], v[16:17], off offset:16 nt
	global_load_dwordx4 v[42:45], v[14:15], off offset:16 nt
	global_load_dwordx4 v[54:57], v[12:13], off nt
	global_load_dwordx4 v[58:61], v[12:13], off offset:2048 nt
	v_add_co_u32_e32 v14, vcc, s36, v10
	s_mov_b64 s[4:5], vcc
	v_add_co_u32_e32 v92, vcc, s37, v10
	v_lshl_add_u64 v[12:13], v[10:11], 0, s[18:19]
	s_nop 0
	v_addc_co_u32_e32 v93, vcc, 0, v11, vcc
	global_load_dwordx4 v[34:37], v[12:13], off offset:16 nt
	global_load_dwordx4 v[46:49], v[92:93], off offset:-4096 nt
	v_addc_co_u32_e64 v15, vcc, 0, v11, s[4:5]
	global_load_dwordx4 v[30:33], v[14:15], off offset:2048 nt
	v_lshl_add_u64 v[94:95], v[10:11], 0, s[24:25]
	v_lshl_add_u64 v[96:97], v[10:11], 0, s[20:21]
	v_lshl_add_u64 v[98:99], v[10:11], 0, s[22:23]
	global_load_dwordx4 v[10:13], v[94:95], off offset:16 nt
	global_load_dwordx4 v[50:53], v[92:93], off nt
	global_load_dwordx4 v[62:65], v[96:97], off offset:16 nt
	global_load_dwordx4 v[38:41], v[98:99], off offset:16 nt
	global_load_dwordx4 v[14:17], v[92:93], off offset:2048 nt
	s_waitcnt vmcnt(15)
	v_pk_mul_f32 v[92:93], v[28:29], v[28:29]
	v_pk_mul_f32 v[94:95], v[26:27], v[26:27]
	s_waitcnt vmcnt(14)
	v_pk_mul_f32 v[96:97], v[24:25], v[24:25]
	v_pk_mul_f32 v[98:99], v[22:23], v[22:23]
	s_waitcnt vmcnt(12)
	v_mul_f32_e32 v84, v7, v7
	v_mul_f32_e32 v100, v9, v9
	v_pk_mov_b32 v[102:103], v[94:95], v[92:93] op_sel:[1,0]
	v_mov_b32_e32 v95, v93
	v_pk_mov_b32 v[92:93], v[98:99], v[96:97] op_sel:[1,0]
	v_mov_b32_e32 v99, v97
	v_mul_f32_e32 v104, v4, v4
	v_mul_f32_e32 v105, v5, v5
	v_pk_fma_f32 v[96:97], v[6:7], v[6:7], v[84:85] op_sel_hi:[1,1,0]
	v_pk_fma_f32 v[100:101], v[8:9], v[8:9], v[100:101] op_sel_hi:[1,1,0]
	v_pk_add_f32 v[94:95], v[102:103], v[94:95]
	v_pk_add_f32 v[92:93], v[92:93], v[98:99]
	v_mul_f32_e32 v112, v2, v2
	v_mul_f32_e32 v113, v3, v3
	v_mov_b32_e32 v97, v104
	v_mov_b32_e32 v101, v105
	v_pk_add_f32 v[94:95], v[94:95], v[94:95] op_sel:[0,1] op_sel_hi:[1,0]
	v_pk_add_f32 v[92:93], v[92:93], v[92:93] op_sel:[0,1] op_sel_hi:[1,0]
	v_pk_add_f32 v[96:97], v[96:97], v[100:101]
	s_waitcnt vmcnt(9)
; __device__ __forceinline__ float wave_sum(float v) {
; #pragma unroll
;     for (int o = 1; o < 64; o <<= 1) v += __shfl_xor(v, o);
;     return v;
; __device__ __forceinline__ void rms_regs_to_bf16(const f32x4 (&v)[16], const float* w, bf16* orow, int lane) {
;     float s = 0.f;
; #pragma unroll
;     for (int j = 0; j < 16; ++j) s += (v[j].x * v[j].x + v[j].y * v[j].y) + (v[j].z * v[j].z + v[j].w * v[j].w);
;     const float rstd = 1.0f / sqrtf(wave_sum(s) * (1.0f / DM) + EPS);
	v_pk_mul_f32 v[100:101], v[56:57], v[56:57]
	v_pk_mul_f32 v[106:107], v[54:55], v[54:55]
	v_mov_b32_e32 v95, v112
	v_mov_b32_e32 v93, v113
	v_pk_mov_b32 v[110:111], v[106:107], v[100:101] op_sel:[1,0]
	v_mov_b32_e32 v107, v101
	v_pk_add_f32 v[92:93], v[94:95], v[92:93]
	v_pk_mul_f32 v[98:99], v[20:21], v[20:21]
	v_pk_mul_f32 v[102:103], v[18:19], v[18:19]
	v_mul_f32_e32 v84, v43, v43
	v_mul_f32_e32 v104, v45, v45
	v_pk_add_f32 v[94:95], v[110:111], v[106:107]
	v_pk_add_f32 v[92:93], v[92:93], v[96:97]
	v_pk_mov_b32 v[108:109], v[102:103], v[98:99] op_sel:[1,0]
	v_mov_b32_e32 v103, v99
	v_pk_fma_f32 v[98:99], v[42:43], v[42:43], v[84:85] op_sel_hi:[1,1,0]
	v_pk_fma_f32 v[104:105], v[44:45], v[44:45], v[104:105] op_sel_hi:[1,1,0]
	s_waitcnt vmcnt(8)
	v_mul_f32_e32 v114, v59, v59
	v_pk_add_f32 v[94:95], v[94:95], v[94:95] op_sel:[0,1] op_sel_hi:[1,0]
	v_pk_add_f32 v[92:93], v[92:93], v[92:93] op_sel:[0,1] op_sel_hi:[1,0]
	v_mul_f32_e32 v99, v60, v60
	v_mul_f32_e32 v105, v61, v61
	v_mov_b32_e32 v95, v114
	v_mul_f32_e32 v93, v58, v58
	v_pk_add_f32 v[98:99], v[98:99], v[104:105]
	v_pk_add_f32 v[92:93], v[92:93], v[94:95]
	v_pk_add_f32 v[100:101], v[108:109], v[102:103]
	v_pk_add_f32 v[92:93], v[92:93], v[98:99]
	v_pk_add_f32 v[94:95], v[100:101], v[100:101] op_sel:[0,1] op_sel_hi:[1,0]
	v_pk_add_f32 v[92:93], v[92:93], v[92:93] op_sel:[0,1] op_sel_hi:[1,0]
	s_waitcnt vmcnt(7)
	v_mul_f32_e32 v95, v35, v35
	v_mul_f32_e32 v93, v34, v34
	s_waitcnt vmcnt(6)
	v_mul_f32_e32 v84, v47, v47
	v_pk_add_f32 v[92:93], v[92:93], v[94:95]
	v_pk_fma_f32 v[94:95], v[46:47], v[46:47], v[84:85] op_sel_hi:[1,1,0]
	v_mul_f32_e32 v84, v49, v49
	v_pk_fma_f32 v[96:97], v[48:49], v[48:49], v[84:85] op_sel_hi:[1,1,0]
	v_mul_f32_e32 v95, v36, v36
	v_mul_f32_e32 v97, v37, v37
	v_pk_add_f32 v[94:95], v[94:95], v[96:97]
	s_waitcnt vmcnt(5)
	v_pk_mul_f32 v[96:97], v[30:31], v[30:31]
	v_pk_add_f32 v[92:93], v[92:93], v[94:95]
	v_pk_mul_f32 v[94:95], v[32:33], v[32:33]
	v_pk_add_f32 v[92:93], v[92:93], v[92:93] op_sel:[0,1] op_sel_hi:[1,0]
	v_pk_mov_b32 v[98:99], v[96:97], v[94:95] op_sel:[1,0]
	v_mov_b32_e32 v97, v95
	v_pk_add_f32 v[94:95], v[98:99], v[96:97]
	s_waitcnt vmcnt(3)
	v_mul_f32_e32 v93, v50, v50
	v_pk_add_f32 v[94:95], v[94:95], v[94:95] op_sel:[0,1] op_sel_hi:[1,0]
	s_waitcnt vmcnt(2)
	v_mul_f32_e32 v84, v63, v63
	v_mul_f32_e32 v95, v51, v51
	v_pk_add_f32 v[92:93], v[92:93], v[94:95]
	v_pk_fma_f32 v[94:95], v[62:63], v[62:63], v[84:85] op_sel_hi:[1,1,0]
	v_mul_f32_e32 v84, v65, v65
	v_pk_fma_f32 v[96:97], v[64:65], v[64:65], v[84:85] op_sel_hi:[1,1,0]
	v_mul_f32_e32 v95, v52, v52
	v_mul_f32_e32 v97, v53, v53
	v_pk_add_f32 v[94:95], v[94:95], v[96:97]
	s_waitcnt vmcnt(1)
	v_pk_mul_f32 v[96:97], v[38:39], v[38:39]
	v_pk_add_f32 v[92:93], v[92:93], v[94:95]
	v_pk_mul_f32 v[94:95], v[40:41], v[40:41]
	s_waitcnt vmcnt(0)
	v_mul_f32_e32 v84, v15, v15
	v_pk_mov_b32 v[98:99], v[96:97], v[94:95] op_sel:[1,0]
	v_mov_b32_e32 v97, v95
	v_pk_add_f32 v[94:95], v[98:99], v[96:97]
	v_pk_fma_f32 v[98:99], v[14:15], v[14:15], v[84:85] op_sel_hi:[1,1,0]
	v_mul_f32_e32 v84, v17, v17
	v_pk_add_f32 v[92:93], v[92:93], v[92:93] op_sel:[0,1] op_sel_hi:[1,0]
	v_pk_add_f32 v[94:95], v[94:95], v[94:95] op_sel:[0,1] op_sel_hi:[1,0]
	v_pk_fma_f32 v[100:101], v[16:17], v[16:17], v[84:85] op_sel_hi:[1,1,0]
	v_mul_f32_e32 v93, v10, v10
	v_mul_f32_e32 v95, v11, v11
	v_mul_f32_e32 v99, v12, v12
	v_mul_f32_e32 v101, v13, v13
	v_pk_add_f32 v[96:97], v[92:93], v[94:95]
	v_pk_add_f32 v[98:99], v[98:99], v[100:101]
	v_pk_add_f32 v[96:97], v[96:97], v[98:99]
	s_nop 0
	v_add_f32_e32 v84, v96, v97
	ds_bpermute_b32 v100, v1, v84
	s_waitcnt lgkmcnt(0)
	v_add_f32_e32 v84, v84, v100
	ds_bpermute_b32 v100, v85, v84
	s_waitcnt lgkmcnt(0)
	v_add_f32_e32 v84, v84, v100
	ds_bpermute_b32 v100, v86, v84
	s_waitcnt lgkmcnt(0)
	v_add_f32_e32 v84, v84, v100
	ds_bpermute_b32 v100, v87, v84
	s_waitcnt lgkmcnt(0)
	v_add_f32_e32 v84, v84, v100
	ds_bpermute_b32 v100, v88, v84
	s_waitcnt lgkmcnt(0)
	v_add_f32_e32 v84, v84, v100
	ds_bpermute_b32 v100, v89, v84
	s_waitcnt lgkmcnt(0)
; __device__ __forceinline__ unsigned cvtpk(float lo, float hi) { f32x2_t v = {lo, hi}; bf16x2_t b = __builtin_convertvector(v, bf16x2_t); return __builtin_bit_cast(unsigned, b); }
; __device__ __forceinline__ void rms_regs_to_bf16(const f32x4 (&v)[16], const float* w, bf16* orow, int lane) {
;     ...
;     const float rstd = 1.0f / sqrtf(wave_sum(s) * (1.0f / DM) + EPS);
;     const f32x4* wr = (const f32x4*)w + 2 * lane; u32x4* o16 = (u32x4*)orow + lane;
; #pragma unroll
;     for (int j = 0; j < 8; ++j) { const f32x4 w0 = wr[128 * j], w1 = wr[128 * j + 1]; const f32x4 a = v[2 * j], b = v[2 * j + 1]; u32x4 o;
;         o.x = cvtpk(a.x * rstd * w0.x, a.y * rstd * w0.y); o.y = cvtpk(a.z * rstd * w0.z, a.w * rstd * w0.w); o.z = cvtpk(b.x * rstd * w1.x, b.y * rstd * w1.y); o.w = cvtpk(b.z * rstd * w1.z, b.w * rstd * w1.w); o16[64 * j] = o; }
	v_add_f32_e32 v84, v84, v100
	v_fmamk_f32 v84, v84, 0x39800000, v90
	v_mul_f32_e32 v100, 0x4f800000, v84
	v_cmp_gt_f32_e32 vcc, s38, v84
	s_nop 1
	v_cndmask_b32_e32 v84, v84, v100, vcc
	v_sqrt_f32_e32 v100, v84
	s_nop 0
	v_add_u32_e32 v101, -1, v100
	v_fma_f32 v102, -v101, v100, v84
	v_cmp_ge_f32_e64 s[4:5], 0, v102
	v_add_u32_e32 v102, 1, v100
	s_nop 0
	v_cndmask_b32_e64 v101, v100, v101, s[4:5]
	v_fma_f32 v100, -v102, v100, v84
	v_cmp_lt_f32_e64 s[4:5], 0, v100
	s_nop 1
	v_cndmask_b32_e64 v100, v101, v102, s[4:5]
	v_mul_f32_e32 v101, 0x37800000, v100
	v_cndmask_b32_e32 v100, v100, v101, vcc
	v_cmp_class_f32_e32 vcc, v84, v91
	s_nop 1
	v_cndmask_b32_e32 v84, v100, v84, vcc
	v_div_scale_f32 v100, s[4:5], v84, v84, 1.0
	v_rcp_f32_e32 v101, v100
	s_lshl_b64 s[4:5], s[30:31], 13
	s_add_u32 s8, s8, s10
	s_addc_u32 s9, s9, s11
	v_fma_f32 v102, -v100, v101, 1.0
	v_fmac_f32_e32 v101, v102, v101
	v_div_scale_f32 v102, vcc, 1.0, v84, 1.0
	v_mul_f32_e32 v103, v102, v101
	v_fma_f32 v104, -v100, v103, v102
	v_fmac_f32_e32 v103, v104, v101
	v_fma_f32 v100, -v100, v103, v102
	v_div_fmas_f32 v100, v100, v101, v103
	v_div_fixup_f32 v84, v100, v84, 1.0
	v_pk_mul_f32 v[26:27], v[26:27], v[84:85] op_sel_hi:[1,0]
	v_pk_mul_f32 v[28:29], v[28:29], v[84:85] op_sel_hi:[1,0]
	v_pk_mul_f32 v[22:23], v[22:23], v[84:85] op_sel_hi:[1,0]
	v_pk_mul_f32 v[24:25], v[24:25], v[84:85] op_sel_hi:[1,0]
	v_pk_mul_f32 v[26:27], v[190:191], v[26:27]
	v_pk_mul_f32 v[28:29], v[192:193], v[28:29]
	v_pk_mul_f32 v[92:93], v[194:195], v[22:23]
	v_pk_mul_f32 v[94:95], v[196:197], v[24:25]
	v_cvt_pk_bf16_f32 v22, v26, v27
	v_cvt_pk_bf16_f32 v23, v28, v29
	v_cvt_pk_bf16_f32 v24, v92, v93
	v_cvt_pk_bf16_f32 v25, v94, v95
	v_lshl_add_u64 v[92:93], v[68:69], 0, s[4:5]
	global_store_dwordx4 v[92:93], v[22:25], off
	s_nop 0
	v_pk_mul_f32 v[6:7], v[6:7], v[84:85] op_sel_hi:[1,0]
	v_pk_mul_f32 v[8:9], v[8:9], v[84:85] op_sel_hi:[1,0]
	v_pk_mul_f32 v[2:3], v[2:3], v[84:85] op_sel_hi:[1,0]
	v_pk_mul_f32 v[4:5], v[4:5], v[84:85] op_sel_hi:[1,0]
	v_pk_mul_f32 v[18:19], v[18:19], v[84:85] op_sel_hi:[1,0]
	v_pk_mul_f32 v[20:21], v[20:21], v[84:85] op_sel_hi:[1,0]
	s_add_u32 s26, s26, s28
	v_pk_mul_f32 v[14:15], v[14:15], v[84:85] op_sel_hi:[1,0]
	v_pk_mul_f32 v[16:17], v[16:17], v[84:85] op_sel_hi:[1,0]
	v_pk_mul_f32 v[10:11], v[10:11], v[84:85] op_sel_hi:[1,0]
	v_pk_mul_f32 v[12:13], v[12:13], v[84:85] op_sel_hi:[1,0]
	s_addc_u32 s27, s27, s29
	s_cmpk_lt_i32 s8, 0x2400
	v_pk_mul_f32 v[6:7], v[198:199], v[6:7]
	v_pk_mul_f32 v[8:9], v[200:201], v[8:9]
	v_pk_mul_f32 v[22:23], v[202:203], v[2:3]
	v_pk_mul_f32 v[24:25], v[204:205], v[4:5]
	v_cvt_pk_bf16_f32 v2, v6, v7
	v_cvt_pk_bf16_f32 v3, v8, v9
	v_cvt_pk_bf16_f32 v4, v22, v23
	v_cvt_pk_bf16_f32 v5, v24, v25
	global_store_dwordx4 v[92:93], v[2:5], off offset:1024
	s_nop 0
	v_pk_mul_f32 v[22:23], v[54:55], v[84:85] op_sel_hi:[1,0]
	v_pk_mul_f32 v[24:25], v[56:57], v[84:85] op_sel_hi:[1,0]
	v_pk_mul_f32 v[26:27], v[42:43], v[84:85] op_sel_hi:[1,0]
	v_pk_mul_f32 v[28:29], v[44:45], v[84:85] op_sel_hi:[1,0]
	v_pk_mul_f32 v[2:3], v[206:207], v[22:23]
	v_pk_mul_f32 v[4:5], v[208:209], v[24:25]
	v_pk_mul_f32 v[6:7], v[210:211], v[26:27]
	v_pk_mul_f32 v[8:9], v[212:213], v[28:29]
	v_cvt_pk_bf16_f32 v2, v2, v3
	v_cvt_pk_bf16_f32 v3, v4, v5
	v_cvt_pk_bf16_f32 v4, v6, v7
	v_cvt_pk_bf16_f32 v5, v8, v9
	global_store_dwordx4 v[92:93], v[2:5], off offset:2048
	s_nop 0
	v_pk_mul_f32 v[22:23], v[58:59], v[84:85] op_sel_hi:[1,0]
	v_pk_mul_f32 v[24:25], v[60:61], v[84:85] op_sel_hi:[1,0]
	v_pk_mul_f32 v[26:27], v[36:37], v[84:85] op_sel_hi:[1,0]
	v_pk_mul_f32 v[2:3], v[22:23], v[214:215]
	v_pk_mul_f32 v[4:5], v[24:25], v[216:217]
	v_pk_mul_f32 v[6:7], v[18:19], v[218:219]
	v_pk_mul_f32 v[8:9], v[20:21], v[220:221]
	v_cvt_pk_bf16_f32 v2, v2, v3
	v_cvt_pk_bf16_f32 v3, v4, v5
	v_cvt_pk_bf16_f32 v4, v6, v7
	v_cvt_pk_bf16_f32 v5, v8, v9
	global_store_dwordx4 v[92:93], v[2:5], off offset:3072
	s_nop 0
	v_pk_mul_f32 v[20:21], v[46:47], v[84:85] op_sel_hi:[1,0]
	v_pk_mul_f32 v[22:23], v[48:49], v[84:85] op_sel_hi:[1,0]
	v_pk_mul_f32 v[24:25], v[34:35], v[84:85] op_sel_hi:[1,0]
	v_add_co_u32_e32 v18, vcc, s33, v92
	v_pk_mul_f32 v[2:3], v[20:21], v[222:223]
	v_pk_mul_f32 v[4:5], v[22:23], v[224:225]
	v_pk_mul_f32 v[6:7], v[24:25], v[226:227]
	v_pk_mul_f32 v[8:9], v[26:27], v[228:229]
	v_addc_co_u32_e32 v19, vcc, 0, v93, vcc
	v_cvt_pk_bf16_f32 v2, v2, v3
	v_cvt_pk_bf16_f32 v3, v4, v5
	v_cvt_pk_bf16_f32 v4, v6, v7
	v_cvt_pk_bf16_f32 v5, v8, v9
	global_store_dwordx4 v[18:19], v[2:5], off
	s_nop 0
	v_pk_mul_f32 v[20:21], v[30:31], v[84:85] op_sel_hi:[1,0]
	v_pk_mul_f32 v[22:23], v[32:33], v[84:85] op_sel_hi:[1,0]
	v_pk_mul_f32 v[24:25], v[62:63], v[84:85] op_sel_hi:[1,0]
	v_pk_mul_f32 v[26:27], v[64:65], v[84:85] op_sel_hi:[1,0]
	v_pk_mul_f32 v[2:3], v[20:21], v[230:231]
	v_pk_mul_f32 v[4:5], v[22:23], v[232:233]
	v_pk_mul_f32 v[6:7], v[24:25], v[234:235]
	v_pk_mul_f32 v[8:9], v[26:27], v[236:237]
	v_cvt_pk_bf16_f32 v2, v2, v3
	v_cvt_pk_bf16_f32 v3, v4, v5
	v_cvt_pk_bf16_f32 v4, v6, v7
	v_cvt_pk_bf16_f32 v5, v8, v9
	global_store_dwordx4 v[18:19], v[2:5], off offset:1024
	s_nop 0
	v_pk_mul_f32 v[20:21], v[50:51], v[84:85] op_sel_hi:[1,0]
	v_pk_mul_f32 v[22:23], v[52:53], v[84:85] op_sel_hi:[1,0]
	v_pk_mul_f32 v[24:25], v[38:39], v[84:85] op_sel_hi:[1,0]
	v_pk_mul_f32 v[26:27], v[40:41], v[84:85] op_sel_hi:[1,0]
	v_pk_mul_f32 v[2:3], v[20:21], v[238:239]
	v_pk_mul_f32 v[4:5], v[22:23], v[240:241]
	v_pk_mul_f32 v[6:7], v[24:25], v[242:243]
	v_pk_mul_f32 v[8:9], v[26:27], v[244:245]
	v_cvt_pk_bf16_f32 v2, v2, v3
	v_cvt_pk_bf16_f32 v3, v4, v5
	v_cvt_pk_bf16_f32 v4, v6, v7
	v_cvt_pk_bf16_f32 v5, v8, v9
	global_store_dwordx4 v[18:19], v[2:5], off offset:2048
	s_nop 2
	v_pk_mul_f32 v[2:3], v[14:15], v[246:247]
	v_pk_mul_f32 v[4:5], v[16:17], v[248:249]
	v_pk_mul_f32 v[6:7], v[10:11], v[250:251]
	v_pk_mul_f32 v[8:9], v[12:13], v[252:253]
	v_cvt_pk_bf16_f32 v2, v2, v3
	v_cvt_pk_bf16_f32 v3, v4, v5
	v_cvt_pk_bf16_f32 v4, v6, v7
	v_cvt_pk_bf16_f32 v5, v8, v9
	global_store_dwordx4 v[18:19], v[2:5], off offset:3072
	s_cbranch_scc0 .LBB0_20
